# v25: prologue residual-stream init: the 4 row loads issued together (was one round trip each)
# baseline (speedup 1.0000x reference)
; __device__ __forceinline__ unsigned pk2(float lo, float hi) { const f32x2_cv v = {lo, hi}; const bf16x2_cv b = __builtin_convertvector(v, bf16x2_cv); return __builtin_bit_cast(unsigned, b); }
; __device__ __forceinline__ void p0_prologue(ArgP ap, unsigned char* lds, int tid) {
;     ...
;         const float* src = nullptr;
;         if (!pad) { if (o < 64) src = ap->in[2] + (size_t)(o - 48) * 1024; else { const int g = tokbase + o - 64; src = (g < 16384) ? ap->in[0] + (size_t)g * 1024 : ap->in[1] + (size_t)(g - 16384) * 1024; } }
;         float s = 0.f;
; #pragma unroll
;         for (int j = 0; j < 4; ++j) { f32x4_t v = (f32x4_t){0.f, 0.f, 0.f, 0.f}; if (src) v = __builtin_nontemporal_load((const f32x4_t*)(src + 4 * lane + 256 * j));
;             s += v[0] * v[0] + v[1] * v[1] + v[2] * v[2] + v[3] * v[3];
;             u32x2_t w; w.x = pk2(v[0], v[1]); w.y = pk2(v[2], v[3]); *(u32x2_t*)(HB + (size_t)r * 1024 + 4 * lane + 256 * j) = w; }
;         s = wave_sum(s); if (lane == 0) ssq0[r] = s;
.LBB0_950:
	s_or_b64 exec, exec, s[12:13]
	v_cmp_ne_u64_e32 vcc, 0, v[2:3]
	v_lshl_add_u64 v[24:25], v[2:3], 0, v[0:1]
	v_mov_b32_e32 v6, 0
	v_mov_b32_e32 v7, 0
	v_mov_b32_e32 v8, 0
	v_mov_b32_e32 v9, 0
	v_mov_b32_e32 v2, 0
	v_mov_b32_e32 v3, 0
	v_mov_b32_e32 v4, 0
	v_mov_b32_e32 v5, 0
	v_mov_b32_e32 v14, 0
	v_mov_b32_e32 v15, 0
	v_mov_b32_e32 v16, 0
	v_mov_b32_e32 v17, 0
	v_mov_b32_e32 v10, 0
	v_mov_b32_e32 v11, 0
	v_mov_b32_e32 v12, 0
	v_mov_b32_e32 v13, 0
	s_and_saveexec_b64 s[12:13], vcc
	global_load_dwordx4 v[6:9], v[24:25], off nt
	global_load_dwordx4 v[2:5], v[24:25], off offset:1024 nt
	global_load_dwordx4 v[14:17], v[24:25], off offset:2048 nt
	global_load_dwordx4 v[10:13], v[24:25], off offset:3072 nt
	s_or_b64 exec, exec, s[12:13]
	s_waitcnt vmcnt(3)
	v_cvt_pk_bf16_f32 v40, v6, v7
	v_cvt_pk_bf16_f32 v41, v8, v9
	global_store_dwordx2 v[22:23], v[40:41], off offset:-1024
	s_waitcnt vmcnt(3)
	v_cvt_pk_bf16_f32 v42, v2, v3
	v_cvt_pk_bf16_f32 v43, v4, v5
	global_store_dwordx2 v[22:23], v[42:43], off offset:-512
	s_waitcnt vmcnt(3)
	v_cvt_pk_bf16_f32 v44, v14, v15
	v_cvt_pk_bf16_f32 v45, v16, v17
	global_store_dwordx2 v[22:23], v[44:45], off
	v_mul_f32_e32 v7, v7, v7
	v_mul_f32_e32 v3, v3, v3
	v_fmac_f32_e32 v7, v6, v6
	v_fmac_f32_e32 v3, v2, v2
	v_fmac_f32_e32 v7, v8, v8
	v_fmac_f32_e32 v3, v4, v4
	v_fmac_f32_e32 v7, v9, v9
	v_fmac_f32_e32 v3, v5, v5
	v_add_f32_e32 v2, v7, v3
	v_mul_f32_e32 v3, v15, v15
	v_fmac_f32_e32 v3, v14, v14
	v_fmac_f32_e32 v3, v16, v16
	v_fmac_f32_e32 v3, v17, v17
	v_add_f32_e32 v2, v2, v3
	s_waitcnt vmcnt(3)
	v_mul_f32_e32 v3, v11, v11
	v_fmac_f32_e32 v3, v10, v10
	v_fmac_f32_e32 v3, v12, v12
	v_fmac_f32_e32 v3, v13, v13
	v_add_f32_e32 v2, v2, v3
	ds_bpermute_b32 v3, v26, v2
	v_cvt_pk_bf16_f32 v4, v10, v11
	v_cvt_pk_bf16_f32 v5, v12, v13
	global_store_dwordx2 v[22:23], v[4:5], off offset:512
	s_waitcnt lgkmcnt(0)
	v_add_f32_e32 v2, v2, v3
	ds_bpermute_b32 v3, v27, v2
	s_waitcnt lgkmcnt(0)
	v_add_f32_e32 v2, v2, v3
	ds_bpermute_b32 v3, v28, v2
	s_waitcnt lgkmcnt(0)
	v_add_f32_e32 v2, v2, v3
	ds_bpermute_b32 v3, v29, v2
	s_waitcnt lgkmcnt(0)
	v_add_f32_e32 v2, v2, v3
	ds_bpermute_b32 v3, v30, v2
	s_waitcnt lgkmcnt(0)
	v_add_f32_e32 v2, v2, v3
	ds_bpermute_b32 v3, v31, v2
	s_and_saveexec_b64 s[12:13], s[36:37]
	s_cbranch_execz .LBB0_933
	s_waitcnt lgkmcnt(0)
	v_add_f32_e32 v2, v2, v3
	global_store_dword v[20:21], v2, off
	s_branch .LBB0_933
